# v12 + sparse-attention phase: per-wave LDS regions moved onto the wave's own NSA score area, block barrier dropped, sparse queries dealt to waves 0-3 (light NSA tiles)
# speedup vs baseline: 1.0185x; 1.0074x over previous
; template <class T> DI T* opqp(T* p) { unsigned long long v = (unsigned long long)p; asm volatile("" : "+s"(v)); return (T*)v; }
; DI int tid_of(int wave_s) { unsigned z = 0; asm volatile("" : "+s"(z)); int l = __builtin_amdgcn_mbcnt_hi(~0u, __builtin_amdgcn_mbcnt_lo(~0u, z)); return wave_s * 64 + l; }
; #define P kparams()
; DI void dsa_sparse_phase(unsigned char* lds, KParamPtr P, int wv) {
;   unsigned char* wsq = opqp(P->ws);
;   const float* tab = (const float*)(lds + LDS_TAB);
;   const int tid = tid_of(wv), lane = tid & 63, wave = tid >> 6;
;   bf16_t* gbuf = (bf16_t*)(lds + LDS_WORK + 4096 + wave * 9216);
;   unsigned short* idL = (unsigned short*)(lds + LDS_WORK + 4096 + wave * 9216 + 8704);
;   __syncthreads();
;   bf16_t* qlat = (bf16_t*)(wsq + OFF_U + U_QLAT);
;   const bf16_t* ckv = (const bf16_t*)(wsq + OFF_MISC + 12 * MiB);
;   const unsigned short* idx = (const unsigned short*)(wsq + OFF_U + U_IDX);
;   const int nw = gridDim.x * 8, gw = blockIdx.x * 8 + wave;
;   const int col = lane & 15, q4 = lane >> 4;
;   const float* tabc = tab + (8 + (col & 7)) * 128;
;   const int rk = 8 * (col >> 2) + (col & 3);
;   const int grow = lane >> 4, gc16 = lane & 15;
;   const bool dealt = (gridDim.x == 256);
;   const int g_lo = dealt ? (int)kSpStart[blockIdx.x >> 3] : 0, g_n = dealt ? (int)kSpStart[(blockIdx.x >> 3) + 1] - g_lo : 0;
.LBB0_1158:
	s_or_b64 exec, exec, s[18:19]
	s_mov_b64 s[4:5], s[64:65]
	s_load_dwordx2 s[6:7], s[4:5], 0xc8
	v_readlane_b32 s4, v254, 46
	v_readlane_b32 s5, v254, 47
	s_mov_b32 s2, 0
	s_and_b64 vcc, exec, s[4:5]
	v_mov_b32_e32 v0, 0
	v_mov_b32_e32 v104, 0
	v_readlane_b32 s24, v255, 11
	s_waitcnt lgkmcnt(0)
	v_readlane_b32 s25, v255, 12
	s_cbranch_vccz .LBB0_1160
	v_readlane_b32 s4, v254, 50
	v_readlane_b32 s5, v254, 51
	s_nop 4
	global_load_ushort v104, v1, s[4:5]

; DI void dsa_sparse_phase(unsigned char* lds, KParamPtr P, int wv) {
;     ...
;   const bool dealt = (gridDim.x == 256);
;   const int g_lo = dealt ? (int)kSpStart[blockIdx.x >> 3] : 0, g_n = dealt ? (int)kSpStart[(blockIdx.x >> 3) + 1] - g_lo : 0;
;   auto qmap = [&](int qi) -> int {
;     const int w8 = qi & 7, blk = (qi >> 3) & 255, rnd = qi >> 11, x = blk & 7;
;     const int gidx = dealt ? g_lo + rnd : rnd * 32 + (blk >> 3);
;     return ((x >> 1) << 13) + (((gidx << 1) + (x & 1)) << 3) + w8;
;   };
;   const int qi_end = dealt ? gw + g_n * nw : NTOK;
;   u32x2 idn = (gw < qi_end) ? *(const u32x2*)(idx + (size_t)qmap(gw) * 256 + lane * 4) : (u32x2){0u, 0u};
;   for (int qi = gw; qi < qi_end; qi += nw) {
.LBB0_1162:
	v_mbcnt_lo_u32_b32 v2, -1, s2
	v_mbcnt_hi_u32_b32 v3, -1, v2
	v_readlane_b32 s4, v254, 0
	v_readlane_b32 s5, v254, 1
	v_readlane_b32 s2, v254, 33
	v_add_u32_e32 v2, s4, v3
	v_ashrrev_i32_e32 v4, 6, v2
	v_add_u32_e32 v2, s2, v4
	v_mul_lo_u32 v0, v0, s24
	v_readlane_b32 s4, v254, 46
	v_add_u32_e32 v0, v0, v2
	v_readlane_b32 s5, v254, 47
	v_mov_b32_e32 v5, 0x8000
	s_nop 0
	v_cndmask_b32_e64 v105, v5, v0, s[4:5]
	v_cmp_gt_u32_e64 s[8:9], 4, v4
	s_mov_b32 s23, 4
	s_nop 1
	v_cndmask_b32_e64 v105, v2, v105, s[8:9]
	v_cmp_lt_i32_e32 vcc, v2, v105
	s_and_saveexec_b64 s[16:17], vcc
	s_cbranch_execz .LBB0_1189
	v_readlane_b32 s8, v254, 48
	v_readlane_b32 s9, v254, 49
	v_ashrrev_i32_e32 v5, 11, v2
	s_mov_b64 s[4:5], -1
	s_and_b64 vcc, exec, s[8:9]
	s_cbranch_vccz .LBB0_1165
	v_bfe_u32 v0, v2, 6, 5
	v_lshl_or_b32 v0, v5, 5, v0
	s_mov_b64 s[4:5], 0

; DI void dsa_sparse_phase(unsigned char* lds, KParamPtr P, int wv) {
;     ...
;   bf16_t* gbuf = (bf16_t*)(lds + LDS_WORK + 4096 + wave * 9216);
;   unsigned short* idL = (unsigned short*)(lds + LDS_WORK + 4096 + wave * 9216 + 8704);
;   __syncthreads();
;   bf16_t* qlat = (bf16_t*)(wsq + OFF_U + U_QLAT);
;   const bf16_t* ckv = (const bf16_t*)(wsq + OFF_MISC + 12 * MiB);
;   const unsigned short* idx = (const unsigned short*)(wsq + OFF_U + U_IDX);
;   const int nw = gridDim.x * 8, gw = blockIdx.x * 8 + wave;
;   const int col = lane & 15, q4 = lane >> 4;
;   const float* tabc = tab + (8 + (col & 7)) * 128;
;   const int rk = 8 * (col >> 2) + (col & 3);
;   const int grow = lane >> 4, gc16 = lane & 15;
;   const bool dealt = (gridDim.x == 256);
;   const int g_lo = dealt ? (int)kSpStart[blockIdx.x >> 3] : 0, g_n = dealt ? (int)kSpStart[(blockIdx.x >> 3) + 1] - g_lo : 0;
;   auto qmap = [&](int qi) -> int {
;     const int w8 = qi & 7, blk = (qi >> 3) & 255, rnd = qi >> 11, x = blk & 7;
;     const int gidx = dealt ? g_lo + rnd : rnd * 32 + (blk >> 3);
;     return ((x >> 1) << 13) + (((gidx << 1) + (x & 1)) << 3) + w8;
;   };
;   const int qi_end = dealt ? gw + g_n * nw : NTOK;
;   u32x2 idn = (gw < qi_end) ? *(const u32x2*)(idx + (size_t)qmap(gw) * 256 + lane * 4) : (u32x2){0u, 0u};
.LBB0_1167:
	v_lshlrev_b32_e32 v6, 9, v2
	v_and_b32_e32 v7, 15, v2
	s_movk_i32 s2, 0x6000
	s_add_u32 s18, s6, 0x1ac00000
	v_and_or_b32 v6, v6, s2, v7
	s_addc_u32 s19, s7, 0
	v_lshl_add_u32 v6, v0, 4, v6
	s_add_u32 s4, s6, 0x16e00000
	v_ashrrev_i32_e32 v7, 31, v6
	v_and_b32_e32 v5, 63, v3
	s_addc_u32 s5, s7, 0
	v_lshlrev_b64 v[6:7], 9, v[6:7]
	v_lshl_add_u64 v[6:7], s[4:5], 0, v[6:7]
	v_lshlrev_b32_e32 v0, 3, v5
	v_lshl_add_u64 v[6:7], v[6:7], 0, v[0:1]
	flat_load_dwordx2 v[96:97], v[6:7]
	s_movk_i32 s2, 0x4000
	v_mul_lo_u32 v8, v4, s2
	v_lshlrev_b32_e32 v4, 9, v3
	v_add_u32_e32 v9, 0, v8
	v_and_b32_e32 v10, 15, v3
	v_and_b32_e32 v4, 0xe00, v4
	v_add_u32_e32 v106, 0, v4
	v_lshlrev_b32_e32 v4, 1, v3
	v_and_b32_e32 v5, 3, v3
	v_add_u32_e32 v107, v9, v0
	v_lshl_add_u64 v[90:91], s[4:5], 0, v[0:1]
	v_lshlrev_b32_e32 v0, 8, v10
	v_bfe_u32 v11, v3, 4, 2
	v_and_or_b32 v12, v4, 24, v5
	v_lshl_add_u64 v[4:5], s[6:7], 0, v[0:1]
	s_mov_b64 s[6:7], 0x12e00000
	v_lshl_add_u64 v[4:5], v[4:5], 0, s[6:7]
	v_lshlrev_b32_e32 v0, 3, v11
	v_and_b32_e32 v6, 48, v3
	v_mov_b32_e32 v7, v1
	v_cmp_gt_u32_e64 s[4:5], 8, v10
	v_lshl_add_u64 v[92:93], v[4:5], 0, v[6:7]
	v_lshlrev_b32_e32 v108, 3, v10
	v_lshl_add_u32 v109, v11, 1, v9
	v_lshl_add_u32 v3, v10, 4, v9
	v_mul_i32_i24_e32 v7, -14, v10
	v_add_u32_e32 v9, v9, v6
	v_mul_u32_u24_e32 v10, 0x880, v11
	v_lshl_add_u64 v[94:95], v[4:5], 0, v[0:1]
	v_mul_u32_u24_e32 v0, 0x110, v11
	v_mul_u32_u24_e32 v4, 0x110, v12
	v_or_b32_e32 v5, v8, v6
	v_readlane_b32 s2, v255, 10
	v_add3_u32 v110, v3, v7, v10
	s_mov_b64 s[20:21], 0
	v_add_u32_e32 v111, s2, v5
	v_add_u32_e32 v112, v3, v0
	v_add_u32_e32 v113, v9, v4
	s_branch .LBB0_1169

; DI void dsa_sparse_phase(unsigned char* lds, KParamPtr P, int wv) {
;     ...
;   for (int qi = gw; qi < qi_end; qi += nw) {
;     const int q = qmap(qi);
;     const int b = q >> 13, tq = q & (SEQ - 1);
;     asm volatile("" ::: "memory");
;     *(u32x2*)(idL + lane * 4) = idn;
;     asm volatile("" ::: "memory");
;     {
;       const int qn = qmap(qi + nw < qi_end ? qi + nw : qi);
;       idn = *(const u32x2*)(idx + (size_t)qn * 256 + lane * 4);
;     }
.LBB0_1173:
	s_waitcnt vmcnt(0) lgkmcnt(0)
	ds_write_b64 v107, v[96:97] offset:20992
	v_add_u32_e32 v114, s23, v2
	s_sub_u32 s23, 0x800, s23
	v_cmp_lt_i32_e32 vcc, v114, v105
	v_readlane_b32 s10, v254, 48
	v_readlane_b32 s11, v254, 49
	v_cndmask_b32_e32 v3, v2, v114, vcc
	v_cmp_ge_i32_e64 s[6:7], v114, v105
	v_ashrrev_i32_e32 v5, 11, v3
	s_mov_b64 s[8:9], -1
	s_and_b64 vcc, exec, s[10:11]
	s_cbranch_vccz .LBB0_1175
	v_bfe_u32 v4, v3, 6, 5
	v_lshl_or_b32 v4, v5, 5, v4
	s_mov_b64 s[8:9], 0
